# attention (large unit): V tile staged by LDS-DMA row-major with chunk swizzle and read with ds_read_b64_tr_b16; removes 8 ds_write_b16 per thread per tile
# speedup vs baseline: 1.0080x; 1.0022x over previous
.LBB0_606:
	s_or_b64 exec, exec, s[10:11]
	v_and_b32_e32 v237, 16, v191
	v_lshlrev_b32_e32 v237, 2, v237
	v_xor_b32_e32 v234, v237, v180
	v_mov_b32_e32 v235, v181
	global_load_dwordx4 v[112:115], v[234:235], off offset:1024
	s_waitcnt vmcnt(1)
	ds_write_b128 v119, v[104:107]
	s_and_saveexec_b64 s[10:11], s[4:5]
	ds_write_b128 v119, v[108:111] offset:8192
	s_or_b64 exec, exec, s[10:11]
	s_sub_i32 s10, 0x1000, s62
	s_ashr_i32 s50, s10, 6
	s_cmp_lt_i32 s50, 1
	s_waitcnt vmcnt(0)
	ds_write_b128 v119, v[112:115] offset:24576
	s_waitcnt lgkmcnt(0)
	s_barrier
	s_cbranch_scc1 .LBB0_633
	v_mov_b32_e32 v14, v121
	v_mov_b32_e32 v15, v121
	v_mov_b32_e32 v0, v121
	v_mov_b32_e32 v1, v121
	v_mov_b32_e32 v2, v121
	v_mov_b32_e32 v3, v121
	v_mov_b32_e32 v4, v121
	v_mov_b32_e32 v5, v121
	v_mov_b32_e32 v6, v121
	v_mov_b32_e32 v7, v121
	v_mov_b32_e32 v8, v121
	v_mov_b32_e32 v9, v121
	v_mov_b32_e32 v10, v121
	v_mov_b32_e32 v11, v121
	v_mov_b32_e32 v12, v121
	v_mov_b32_e32 v13, v121
	v_mov_b32_e32 v143, 0
	v_mov_b64_e32 v[30:31], v[14:15]
	s_or_b32 s51, s47, 31
	s_sub_i32 s62, 0, s50
	s_mov_b32 s63, 1
	s_mov_b32 s64, 63
	v_mov_b64_e32 v[28:29], v[12:13]
	v_mov_b64_e32 v[26:27], v[10:11]
	v_mov_b64_e32 v[24:25], v[8:9]
	v_mov_b64_e32 v[22:23], v[6:7]
	v_mov_b64_e32 v[20:21], v[4:5]
	v_mov_b64_e32 v[18:19], v[2:3]
	v_mov_b64_e32 v[16:17], v[0:1]
	v_mov_b32_e32 v141, 0
	v_mov_b32_e32 v32, 0
	v_mov_b32_e32 v33, v143
	v_mov_b32_e32 v34, v143
	v_mov_b32_e32 v35, v143
	v_mov_b32_e32 v36, v143
	v_mov_b32_e32 v37, v143
	v_mov_b32_e32 v38, v143
	v_mov_b32_e32 v39, v143
	v_mov_b32_e32 v40, v143
	v_mov_b32_e32 v41, v143
	v_mov_b32_e32 v42, v143
	v_mov_b32_e32 v43, v143
	v_mov_b32_e32 v44, v143
	v_mov_b32_e32 v45, v143
	v_mov_b32_e32 v46, v143
	v_mov_b32_e32 v47, v143
	v_bfe_u32 v232, v191, 2, 2
	v_bfe_u32 v233, v191, 5, 1
	v_lshl_add_u32 v233, v233, 2, v232
	v_lshlrev_b32_e32 v238, 7, v233
	v_bfe_u32 v233, v191, 4, 1
	v_bfe_u32 v234, v191, 1, 1
	v_lshl_or_b32 v233, v233, 1, v234
	v_lshrrev_b32_e32 v232, 1, v232
	v_lshlrev_b32_e32 v232, 2, v232
	v_xor_b32_e32 v233, v233, v232
	v_lshl_add_u32 v238, v233, 4, v238
	v_and_b32_e32 v232, 1, v191
	v_lshl_add_u32 v238, v232, 3, v238
	v_xor_b32_e32 v239, 64, v238
	v_readfirstlane_b32 s99, v119
	v_xor_b32_e32 v170, v237, v170
	s_branch .LBB0_612
.LBB0_610:
	s_or_b64 exec, exec, s[10:11]
	s_waitcnt vmcnt(0)
.LBB0_611:
	s_add_i32 s63, s63, 1
	s_add_i32 s64, s64, 64
	s_add_i32 s10, s62, s63
	v_lshl_add_u64 v[170:171], v[170:171], 0, s[40:41]
	v_lshl_add_u64 v[172:173], v[172:173], 0, s[42:43]
	s_cmp_eq_u32 s10, 1
	v_lshl_add_u64 v[174:175], v[174:175], 0, s[40:41]
	s_waitcnt lgkmcnt(0)
	s_barrier
	s_cbranch_scc1 .LBB0_634

.LBB0_615:
	s_or_b64 exec, exec, s[10:11]
	s_and_b32 s10, s63, 1
	s_mulk_i32 s10, 0x2200
	s_add_i32 s10, s10, s99
	s_add_i32 m0, s10, 0x6000
	s_nop 0
	global_load_lds_dwordx4 v[170:171], off

.LBB0_628:
	s_mul_i32 s10, s65, 0x2200
	v_add_u32_e32 v232, s10, v238
	v_add_u32_e32 v233, s10, v239
	ds_read_b64_tr_b16 v[212:213], v232 offset:24576
	ds_read_b64_tr_b16 v[214:215], v232 offset:25600
	ds_read_b64_tr_b16 v[216:217], v232 offset:26624
	ds_read_b64_tr_b16 v[218:219], v232 offset:27648
	ds_read_b64_tr_b16 v[220:221], v233 offset:24576
	ds_read_b64_tr_b16 v[222:223], v233 offset:25600
	ds_read_b64_tr_b16 v[224:225], v233 offset:26624
	ds_read_b64_tr_b16 v[226:227], v233 offset:27648
	ds_read_b64_tr_b16 v[228:229], v232 offset:28672
	ds_read_b64_tr_b16 v[230:231], v232 offset:29696
	v_exp_f32_e32 v176, v64
	v_exp_f32_e32 v177, v65
	v_exp_f32_e32 v180, v48
	v_exp_f32_e32 v181, v49
	v_exp_f32_e32 v178, v66
	v_exp_f32_e32 v179, v67
	v_exp_f32_e32 v186, v50
	v_exp_f32_e32 v187, v51
	v_exp_f32_e32 v184, v68
	v_exp_f32_e32 v185, v69
	v_pk_add_f32 v[48:49], v[180:181], v[176:177]
	v_exp_f32_e32 v188, v52
	v_exp_f32_e32 v189, v53
	v_pk_add_f32 v[48:49], v[178:179], v[48:49]
	v_exp_f32_e32 v192, v70
	v_exp_f32_e32 v193, v71
	v_pk_add_f32 v[48:49], v[186:187], v[48:49]
	v_exp_f32_e32 v194, v54
	v_exp_f32_e32 v195, v55
	v_pk_add_f32 v[48:49], v[184:185], v[48:49]
	v_exp_f32_e32 v196, v72
	v_exp_f32_e32 v197, v73
	v_pk_add_f32 v[48:49], v[188:189], v[48:49]
	v_exp_f32_e32 v198, v56
	v_exp_f32_e32 v199, v57
	v_pk_add_f32 v[48:49], v[192:193], v[48:49]
	v_exp_f32_e32 v200, v74
	v_exp_f32_e32 v201, v75
	v_pk_add_f32 v[48:49], v[194:195], v[48:49]
	v_exp_f32_e32 v202, v58
	v_exp_f32_e32 v203, v59
	v_pk_add_f32 v[48:49], v[196:197], v[48:49]
	v_exp_f32_e32 v204, v76
	v_exp_f32_e32 v205, v77
	v_pk_add_f32 v[48:49], v[198:199], v[48:49]
	v_exp_f32_e32 v206, v60
	v_exp_f32_e32 v207, v61
	v_pk_add_f32 v[48:49], v[200:201], v[48:49]
	v_exp_f32_e32 v208, v78
	v_exp_f32_e32 v209, v79
	v_pk_add_f32 v[48:49], v[202:203], v[48:49]
	v_exp_f32_e32 v210, v62
	v_exp_f32_e32 v211, v63
	v_pk_add_f32 v[48:49], v[204:205], v[48:49]
	v_pk_add_f32 v[48:49], v[206:207], v[48:49]
	v_pk_add_f32 v[48:49], v[208:209], v[48:49]
	v_pk_add_f32 v[48:49], v[210:211], v[48:49]
	v_pk_add_f32 v[48:49], v[48:49], v[48:49] op_sel:[0,1] op_sel_hi:[1,0]
	v_cvt_pk_bf16_f32 v176, v176, v177
	v_mov_b32_e32 v49, v48
	s_nop 1
	v_permlane32_swap_b32_e32 v48, v49
	v_add_f32_e32 v145, v48, v49
	ds_read_b64_tr_b16 v[68:69], v233 offset:28672
	ds_read_b64_tr_b16 v[70:71], v233 offset:29696
	ds_read_b64_tr_b16 v[72:73], v232 offset:30720
	ds_read_b64_tr_b16 v[74:75], v232 offset:31744
	ds_read_b64_tr_b16 v[76:77], v233 offset:30720
	ds_read_b64_tr_b16 v[78:79], v233 offset:31744
	v_cvt_pk_bf16_f32 v177, v178, v179
	v_cvt_pk_bf16_f32 v178, v184, v185
	v_cvt_pk_bf16_f32 v179, v192, v193
	v_cvt_pk_bf16_f32 v184, v180, v181
	v_cvt_pk_bf16_f32 v185, v186, v187
	v_cvt_pk_bf16_f32 v186, v188, v189
	v_cvt_pk_bf16_f32 v187, v194, v195
	v_cvt_pk_bf16_f32 v192, v196, v197
	v_cvt_pk_bf16_f32 v193, v200, v201
	v_cvt_pk_bf16_f32 v194, v204, v205
	v_cvt_pk_bf16_f32 v195, v208, v209
	v_cvt_pk_bf16_f32 v196, v198, v199
	v_cvt_pk_bf16_f32 v197, v202, v203
	v_cvt_pk_bf16_f32 v198, v206, v207
	v_cvt_pk_bf16_f32 v199, v210, v211
	s_setprio 1
	s_waitcnt lgkmcnt(14)
	v_mfma_f32_32x32x16_bf16 v[0:15], v[176:179], v[212:215], v[0:15]
	v_add_f32_e32 v141, v141, v145
	s_waitcnt lgkmcnt(10)
	v_mfma_f32_32x32x16_bf16 v[16:31], v[176:179], v[220:223], v[16:31]
	v_mfma_f32_32x32x16_bf16 v[0:15], v[192:195], v[216:219], v[0:15]
	s_waitcnt lgkmcnt(8)
	v_mfma_f32_32x32x16_bf16 v[16:31], v[192:195], v[224:227], v[16:31]
	s_waitcnt lgkmcnt(6)
	v_mfma_f32_32x32x16_bf16 v[0:15], v[184:187], v[228:231], v[0:15]
	s_waitcnt lgkmcnt(4)
	v_mfma_f32_32x32x16_bf16 v[16:31], v[184:187], v[68:71], v[16:31]
	s_waitcnt lgkmcnt(2)
	v_mfma_f32_32x32x16_bf16 v[0:15], v[196:199], v[72:75], v[0:15]
	s_waitcnt lgkmcnt(0)
	v_mfma_f32_32x32x16_bf16 v[16:31], v[196:199], v[76:79], v[16:31]
	s_setprio 0

	.amdhsa_kernel _Z8mega_fwd6Params
		.amdhsa_group_segment_fixed_size 0
		.amdhsa_private_segment_fixed_size 0
		.amdhsa_kernarg_size 520
		.amdhsa_user_sgpr_count 2
		.amdhsa_user_sgpr_dispatch_ptr 0
		.amdhsa_user_sgpr_queue_ptr 0
		.amdhsa_user_sgpr_kernarg_segment_ptr 1
		.amdhsa_user_sgpr_dispatch_id 0
		.amdhsa_user_sgpr_kernarg_preload_length 0
		.amdhsa_user_sgpr_kernarg_preload_offset 0
		.amdhsa_user_sgpr_private_segment_size 0
		.amdhsa_uses_dynamic_stack 0
		.amdhsa_enable_private_segment 0
		.amdhsa_system_sgpr_workgroup_id_x 1
		.amdhsa_system_sgpr_workgroup_id_y 0
		.amdhsa_system_sgpr_workgroup_id_z 0
		.amdhsa_system_sgpr_workgroup_info 0
		.amdhsa_system_vgpr_workitem_id 2
		.amdhsa_next_free_vgpr 240
		.amdhsa_next_free_sgpr 102
		.amdhsa_accum_offset 240
		.amdhsa_reserve_vcc 1
		.amdhsa_float_round_mode_32 0
		.amdhsa_float_round_mode_16_64 0
		.amdhsa_float_denorm_mode_32 3
		.amdhsa_float_denorm_mode_16_64 3
		.amdhsa_dx10_clamp 1
		.amdhsa_ieee_mode 1
		.amdhsa_fp16_overflow 0
		.amdhsa_tg_split 0
		.amdhsa_exception_fp_ieee_invalid_op 0
		.amdhsa_exception_fp_denorm_src 0
		.amdhsa_exception_fp_ieee_div_zero 0
		.amdhsa_exception_fp_ieee_overflow 0
		.amdhsa_exception_fp_ieee_underflow 0
		.amdhsa_exception_fp_ieee_inexact 0
		.amdhsa_exception_int_div_zero 0
	.end_amdhsa_kernel

amdhsa.kernels:
  - .agpr_count:     0
    .args:
      - .offset:         0
        .size:           264
        .value_kind:     by_value
      - .offset:         264
        .size:           4
        .value_kind:     hidden_block_count_x
      - .offset:         268
        .size:           4
        .value_kind:     hidden_block_count_y
      - .offset:         272
        .size:           4
        .value_kind:     hidden_block_count_z
      - .offset:         276
        .size:           2
        .value_kind:     hidden_group_size_x
      - .offset:         278
        .size:           2
        .value_kind:     hidden_group_size_y
      - .offset:         280
        .size:           2
        .value_kind:     hidden_group_size_z
      - .offset:         282
        .size:           2
        .value_kind:     hidden_remainder_x
      - .offset:         284
        .size:           2
        .value_kind:     hidden_remainder_y
      - .offset:         286
        .size:           2
        .value_kind:     hidden_remainder_z
      - .offset:         304
        .size:           8
        .value_kind:     hidden_global_offset_x
      - .offset:         312
        .size:           8
        .value_kind:     hidden_global_offset_y
      - .offset:         320
        .size:           8
        .value_kind:     hidden_global_offset_z
      - .offset:         328
        .size:           2
        .value_kind:     hidden_grid_dims
      - .offset:         352
        .size:           8
        .value_kind:     hidden_multigrid_sync_arg
      - .offset:         384
        .size:           4
        .value_kind:     hidden_dynamic_lds_size
    .group_segment_fixed_size: 0
    .kernarg_segment_align: 8
    .kernarg_segment_size: 520
    .language:       OpenCL C
    .language_version:
      - 2
      - 0
    .max_flat_workgroup_size: 512
    .name:           _Z8mega_fwd6Params
    .private_segment_fixed_size: 0
    .sgpr_count:     108
    .sgpr_spill_count: 65
    .symbol:         _Z8mega_fwd6Params.kd
    .uniform_work_group_size: 1
    .uses_dynamic_stack: false
    .vgpr_count:     240
    .vgpr_spill_count: 0
    .wavefront_size: 64
